# spatial gating: LayerNorm gain/bias of a half-tile loaded once in the preamble instead of with every half-tile (24 fewer VMEM loads per loop trip)
# baseline (speedup 1.0000x reference)
.LBB0_365:
	ds_read_b128 v[64:67], v207
	ds_read_b128 v[56:59], v207 offset:16
	ds_read_b128 v[60:63], v207 offset:512
	ds_read_b128 v[52:55], v207 offset:528
	s_waitcnt vmcnt(12)
	v_lshlrev_b32_e32 v0, 16, v4
	v_and_b32_e32 v68, 0xffff0000, v4
	v_lshlrev_b32_e32 v72, 16, v6
	v_and_b32_e32 v73, 0xffff0000, v6
	v_lshlrev_b32_e32 v70, 16, v7
	v_and_b32_e32 v71, 0xffff0000, v7
	v_lshlrev_b32_e32 v2, 16, v5
	v_and_b32_e32 v3, 0xffff0000, v5
	s_waitcnt lgkmcnt(3)
	v_sub_f32_e32 v69, v68, v65
	v_sub_f32_e32 v68, v0, v64
	s_waitcnt lgkmcnt(2)
	v_sub_f32_e32 v71, v71, v59
	v_sub_f32_e32 v70, v70, v58
	v_sub_f32_e32 v73, v73, v57
	v_sub_f32_e32 v72, v72, v56
	v_sub_f32_e32 v3, v3, v67
	v_sub_f32_e32 v2, v2, v66
	s_waitcnt lgkmcnt(1)
	v_pk_mul_f32 v[68:69], v[60:61], v[68:69]
	s_waitcnt lgkmcnt(0)
	v_pk_mul_f32 v[72:73], v[52:53], v[72:73]
	v_pk_mul_f32 v[70:71], v[54:55], v[70:71]
	v_pk_mul_f32 v[2:3], v[62:63], v[2:3]
	v_pk_fma_f32 v[68:69], v[148:149], v[68:69], v[152:153] op_sel_hi:[0,1,0]
	v_pk_fma_f32 v[74:75], v[148:149], v[70:71], v[152:153] op_sel_hi:[0,1,0]
	v_pk_fma_f32 v[70:71], v[148:149], v[72:73], v[152:153] op_sel_hi:[0,1,0]
	v_pk_fma_f32 v[2:3], v[148:149], v[2:3], v[152:153] op_sel_hi:[0,1,0]
	v_cvt_pk_bf16_f32 v68, v68, v69
	v_cvt_pk_bf16_f32 v69, v2, v3
	v_cvt_pk_bf16_f32 v70, v70, v71
	v_cvt_pk_bf16_f32 v71, v74, v75
	v_add_u32_e32 v0, v149, v163
	ds_write_b128 v0, v[68:71] offset:34816
	s_nop 0
	v_lshlrev_b32_e32 v0, 16, v8
	v_and_b32_e32 v68, 0xffff0000, v8
	v_lshlrev_b32_e32 v72, 16, v10
	v_and_b32_e32 v73, 0xffff0000, v10
	v_lshlrev_b32_e32 v70, 16, v11
	v_and_b32_e32 v71, 0xffff0000, v11
	v_lshlrev_b32_e32 v2, 16, v9
	v_and_b32_e32 v3, 0xffff0000, v9
	v_sub_f32_e32 v69, v68, v65
	v_sub_f32_e32 v68, v0, v64
	v_sub_f32_e32 v71, v71, v59
	v_sub_f32_e32 v70, v70, v58
	v_sub_f32_e32 v73, v73, v57
	v_sub_f32_e32 v72, v72, v56
	v_sub_f32_e32 v3, v3, v67
	v_sub_f32_e32 v2, v2, v66
	v_pk_mul_f32 v[68:69], v[60:61], v[68:69]
	v_pk_mul_f32 v[72:73], v[52:53], v[72:73]
	v_pk_mul_f32 v[70:71], v[54:55], v[70:71]
	v_pk_mul_f32 v[2:3], v[62:63], v[2:3]
	s_nop 0
	v_pk_fma_f32 v[68:69], v[160:161], v[68:69], v[162:163] op_sel_hi:[0,1,0]
	v_pk_fma_f32 v[74:75], v[160:161], v[70:71], v[162:163] op_sel_hi:[0,1,0]
	v_pk_fma_f32 v[70:71], v[160:161], v[72:73], v[162:163] op_sel_hi:[0,1,0]
	v_pk_fma_f32 v[2:3], v[160:161], v[2:3], v[162:163] op_sel_hi:[0,1,0]
	v_cvt_pk_bf16_f32 v68, v68, v69
	v_cvt_pk_bf16_f32 v69, v2, v3
	v_cvt_pk_bf16_f32 v70, v70, v71
	v_cvt_pk_bf16_f32 v71, v74, v75
	v_add_u32_e32 v0, v149, v171
	ds_write_b128 v0, v[68:71] offset:34816
	s_nop 0
	v_lshlrev_b32_e32 v0, 16, v12
	v_and_b32_e32 v68, 0xffff0000, v12
	v_lshlrev_b32_e32 v72, 16, v14
	v_and_b32_e32 v73, 0xffff0000, v14
	v_lshlrev_b32_e32 v70, 16, v15
	v_and_b32_e32 v71, 0xffff0000, v15
	v_lshlrev_b32_e32 v2, 16, v13
	v_and_b32_e32 v3, 0xffff0000, v13
	v_sub_f32_e32 v69, v68, v65
	v_sub_f32_e32 v68, v0, v64
	v_sub_f32_e32 v71, v71, v59
	v_sub_f32_e32 v70, v70, v58
	v_sub_f32_e32 v73, v73, v57
	v_sub_f32_e32 v72, v72, v56
	v_sub_f32_e32 v3, v3, v67
	v_sub_f32_e32 v2, v2, v66
	v_pk_mul_f32 v[68:69], v[60:61], v[68:69]
	v_pk_mul_f32 v[72:73], v[52:53], v[72:73]
	v_pk_mul_f32 v[70:71], v[54:55], v[70:71]
	v_pk_mul_f32 v[2:3], v[62:63], v[2:3]
	v_pk_fma_f32 v[68:69], v[170:171], v[68:69], v[174:175] op_sel_hi:[0,1,0]
	v_pk_fma_f32 v[74:75], v[170:171], v[70:71], v[174:175] op_sel_hi:[0,1,0]
	v_pk_fma_f32 v[70:71], v[170:171], v[72:73], v[174:175] op_sel_hi:[0,1,0]
	v_pk_fma_f32 v[2:3], v[170:171], v[2:3], v[174:175] op_sel_hi:[0,1,0]
	v_cvt_pk_bf16_f32 v68, v68, v69
	v_cvt_pk_bf16_f32 v69, v2, v3
	v_cvt_pk_bf16_f32 v70, v70, v71
	v_cvt_pk_bf16_f32 v71, v74, v75
	v_add_u32_e32 v0, v149, v175
	ds_write_b128 v0, v[68:71] offset:34816
	s_nop 0
	v_lshlrev_b32_e32 v0, 16, v16
	v_and_b32_e32 v68, 0xffff0000, v16
	v_lshlrev_b32_e32 v72, 16, v18
	v_and_b32_e32 v73, 0xffff0000, v18
	v_lshlrev_b32_e32 v70, 16, v19
	v_and_b32_e32 v71, 0xffff0000, v19
	v_lshlrev_b32_e32 v2, 16, v17
	v_and_b32_e32 v3, 0xffff0000, v17
	v_sub_f32_e32 v69, v68, v65
	v_sub_f32_e32 v68, v0, v64
	v_sub_f32_e32 v71, v71, v59
	v_sub_f32_e32 v70, v70, v58
	v_sub_f32_e32 v73, v73, v57
	v_sub_f32_e32 v72, v72, v56
	v_sub_f32_e32 v3, v3, v67
	v_sub_f32_e32 v2, v2, v66
	v_pk_mul_f32 v[68:69], v[60:61], v[68:69]
	v_pk_mul_f32 v[72:73], v[52:53], v[72:73]
	v_pk_mul_f32 v[70:71], v[54:55], v[70:71]
	v_pk_mul_f32 v[2:3], v[62:63], v[2:3]
	s_nop 0
	v_pk_fma_f32 v[68:69], v[182:183], v[68:69], v[186:187] op_sel_hi:[0,1,0]
	v_pk_fma_f32 v[74:75], v[182:183], v[70:71], v[186:187] op_sel_hi:[0,1,0]
	v_pk_fma_f32 v[70:71], v[182:183], v[72:73], v[186:187] op_sel_hi:[0,1,0]
	v_pk_fma_f32 v[2:3], v[182:183], v[2:3], v[186:187] op_sel_hi:[0,1,0]
	v_cvt_pk_bf16_f32 v68, v68, v69
	v_cvt_pk_bf16_f32 v69, v2, v3
	v_cvt_pk_bf16_f32 v70, v70, v71
	v_cvt_pk_bf16_f32 v71, v74, v75
	v_add_u32_e32 v0, v149, v183
	ds_write_b128 v0, v[68:71] offset:34816
	s_nop 0
	v_lshlrev_b32_e32 v0, 16, v20
	v_and_b32_e32 v68, 0xffff0000, v20
	v_lshlrev_b32_e32 v72, 16, v22
	v_and_b32_e32 v73, 0xffff0000, v22
	v_lshlrev_b32_e32 v70, 16, v23
	v_and_b32_e32 v71, 0xffff0000, v23
	v_lshlrev_b32_e32 v2, 16, v21
	v_and_b32_e32 v3, 0xffff0000, v21
	v_sub_f32_e32 v69, v68, v65
	v_sub_f32_e32 v68, v0, v64
	v_sub_f32_e32 v71, v71, v59
	v_sub_f32_e32 v70, v70, v58
	v_sub_f32_e32 v73, v73, v57
	v_sub_f32_e32 v72, v72, v56
	v_sub_f32_e32 v3, v3, v67
	v_sub_f32_e32 v2, v2, v66
	v_pk_mul_f32 v[68:69], v[60:61], v[68:69]
	v_pk_mul_f32 v[72:73], v[52:53], v[72:73]
	v_pk_mul_f32 v[70:71], v[54:55], v[70:71]
	v_pk_mul_f32 v[2:3], v[62:63], v[2:3]
	v_pk_fma_f32 v[68:69], v[194:195], v[68:69], v[198:199] op_sel_hi:[0,1,0]
	v_pk_fma_f32 v[74:75], v[194:195], v[70:71], v[198:199] op_sel_hi:[0,1,0]
	v_pk_fma_f32 v[70:71], v[194:195], v[72:73], v[198:199] op_sel_hi:[0,1,0]
	v_pk_fma_f32 v[2:3], v[194:195], v[2:3], v[198:199] op_sel_hi:[0,1,0]
	v_cvt_pk_bf16_f32 v68, v68, v69
	v_cvt_pk_bf16_f32 v69, v2, v3
	v_cvt_pk_bf16_f32 v70, v70, v71
	v_cvt_pk_bf16_f32 v71, v74, v75
	v_add_u32_e32 v0, v149, v187
	ds_write_b128 v0, v[68:71] offset:34816
	s_nop 0
	v_lshlrev_b32_e32 v69, 16, v30
	v_and_b32_e32 v70, 0xffff0000, v30
	v_lshlrev_b32_e32 v71, 16, v31
	v_and_b32_e32 v72, 0xffff0000, v31
	v_lshlrev_b32_e32 v0, 16, v28
	v_and_b32_e32 v68, 0xffff0000, v28
	v_lshlrev_b32_e32 v2, 16, v29
	v_and_b32_e32 v3, 0xffff0000, v29
	v_sub_f32_e32 v59, v72, v59
	v_sub_f32_e32 v58, v71, v58
	v_sub_f32_e32 v57, v70, v57
	v_sub_f32_e32 v56, v69, v56
	v_sub_f32_e32 v3, v3, v67
	v_sub_f32_e32 v2, v2, v66
	v_sub_f32_e32 v65, v68, v65
	v_sub_f32_e32 v64, v0, v64
	v_pk_mul_f32 v[52:53], v[52:53], v[56:57]
	v_pk_mul_f32 v[54:55], v[54:55], v[58:59]
	v_pk_mul_f32 v[60:61], v[60:61], v[64:65]
	v_pk_mul_f32 v[2:3], v[62:63], v[2:3]
	s_nop 0
	v_pk_fma_f32 v[56:57], v[206:207], v[54:55], v[208:209] op_sel_hi:[0,1,0]
	v_pk_fma_f32 v[54:55], v[206:207], v[52:53], v[208:209] op_sel_hi:[0,1,0]
	v_add_u32_e32 v0, v149, v195
	v_pk_fma_f32 v[2:3], v[206:207], v[2:3], v[208:209] op_sel_hi:[0,1,0]
	v_pk_fma_f32 v[60:61], v[206:207], v[60:61], v[208:209] op_sel_hi:[0,1,0]
	v_cvt_pk_bf16_f32 v52, v60, v61
	v_cvt_pk_bf16_f32 v53, v2, v3
	v_cvt_pk_bf16_f32 v54, v54, v55
	v_cvt_pk_bf16_f32 v55, v56, v57
	ds_write_b128 v0, v[52:55] offset:34816
	s_waitcnt lgkmcnt(0)
	s_barrier
	s_add_i32 s23, s22, -1
	s_cmp_ge_i32 s23, s3
	s_cbranch_scc1 .LBB0_367
	s_add_i32 s11, s2, s10
	v_mad_i64_i32 v[2:3], s[24:25], s11, v241, v[142:143]
	v_mad_i64_i32 v[4:5], s[24:25], s11, v241, v[150:151]
	v_lshlrev_b64 v[2:3], 8, v[2:3]
	v_lshlrev_b64 v[4:5], 8, v[4:5]
	v_lshl_add_u64 v[2:3], v[140:141], 0, v[2:3]
	v_lshl_add_u64 v[8:9], v[140:141], 0, v[4:5]
	s_nop 0
	s_nop 0
	global_load_dwordx4 v[4:7], v[2:3], off
	s_nop 0
	global_load_dwordx4 v[8:11], v[8:9], off
	s_nop 0
	s_nop 0
	s_nop 0
	v_mad_i64_i32 v[2:3], s[24:25], s11, v241, v[158:159]
	v_mad_i64_i32 v[12:13], s[24:25], s11, v241, v[168:169]
	v_lshlrev_b64 v[2:3], 8, v[2:3]
	v_lshlrev_b64 v[12:13], 8, v[12:13]
	v_lshl_add_u64 v[2:3], v[140:141], 0, v[2:3]
	v_lshl_add_u64 v[16:17], v[140:141], 0, v[12:13]
	s_nop 0
	s_nop 0
	global_load_dwordx4 v[12:15], v[2:3], off
	s_nop 0
	global_load_dwordx4 v[16:19], v[16:17], off
	s_nop 0
	s_nop 0
	s_nop 0
	v_mad_i64_i32 v[2:3], s[24:25], s11, v241, v[178:179]
	v_mad_i64_i32 v[20:21], s[24:25], s11, v241, v[188:189]
	v_lshlrev_b64 v[2:3], 8, v[2:3]
	v_lshlrev_b64 v[20:21], 8, v[20:21]
	v_lshl_add_u64 v[2:3], v[140:141], 0, v[2:3]
	v_lshl_add_u64 v[28:29], v[140:141], 0, v[20:21]
	s_nop 0
	s_nop 0
	global_load_dwordx4 v[20:23], v[2:3], off
	s_nop 0
	global_load_dwordx4 v[28:31], v[28:29], off
	s_nop 0
	s_nop 0
	s_nop 0

.LBB0_462:
	s_nop 6
	v_pk_add_f32 v[52:53], v[230:231], v[92:93]
	v_pk_add_f32 v[54:55], v[230:231], v[64:65]
	v_pk_add_f32 v[2:3], v[244:245], v[94:95]
	v_pk_add_f32 v[56:57], v[244:245], v[66:67]
	v_cvt_pk_bf16_f32 v52, v52, v53
	v_cvt_pk_bf16_f32 v53, v2, v3
	v_cvt_pk_bf16_f32 v54, v54, v55
	v_lshlrev_b32_e32 v0, 16, v24
	v_cvt_pk_bf16_f32 v55, v56, v57
	global_store_dwordx4 v[248:249], v[52:55], off offset:320
	s_waitcnt vmcnt(12)
	ds_read_b128 v[64:67], v207
	ds_read_b128 v[56:59], v207 offset:16
	ds_read_b128 v[60:63], v207 offset:512
	ds_read_b128 v[52:55], v207 offset:528
	v_and_b32_e32 v68, 0xffff0000, v24
	v_lshlrev_b32_e32 v72, 16, v26
	v_and_b32_e32 v73, 0xffff0000, v26
	v_lshlrev_b32_e32 v70, 16, v27
	v_and_b32_e32 v71, 0xffff0000, v27
	v_lshlrev_b32_e32 v2, 16, v25
	v_and_b32_e32 v3, 0xffff0000, v25
	s_waitcnt lgkmcnt(3)
	v_sub_f32_e32 v69, v68, v65
	v_sub_f32_e32 v68, v0, v64
	s_waitcnt lgkmcnt(2)
	v_sub_f32_e32 v71, v71, v59
	v_sub_f32_e32 v70, v70, v58
	v_sub_f32_e32 v73, v73, v57
	v_sub_f32_e32 v72, v72, v56
	v_sub_f32_e32 v3, v3, v67
	v_sub_f32_e32 v2, v2, v66
	s_waitcnt lgkmcnt(1)
	v_pk_mul_f32 v[68:69], v[68:69], v[60:61]
	s_waitcnt lgkmcnt(0)
	v_pk_mul_f32 v[72:73], v[72:73], v[52:53]
	v_pk_mul_f32 v[70:71], v[70:71], v[54:55]
	v_pk_mul_f32 v[2:3], v[2:3], v[62:63]
	v_pk_fma_f32 v[68:69], v[202:203], v[68:69], v[204:205] op_sel_hi:[0,1,0]
	v_pk_fma_f32 v[74:75], v[202:203], v[70:71], v[204:205] op_sel_hi:[0,1,0]
	v_pk_fma_f32 v[70:71], v[202:203], v[72:73], v[204:205] op_sel_hi:[0,1,0]
	v_pk_fma_f32 v[2:3], v[202:203], v[2:3], v[204:205] op_sel_hi:[0,1,0]
	v_cvt_pk_bf16_f32 v68, v68, v69
	v_cvt_pk_bf16_f32 v69, v2, v3
	v_cvt_pk_bf16_f32 v70, v70, v71
	v_cvt_pk_bf16_f32 v71, v74, v75
	v_add_u32_e32 v0, v161, v163
	ds_write_b128 v0, v[68:71]
	v_lshlrev_b32_e32 v0, 16, v32
	v_and_b32_e32 v68, 0xffff0000, v32
	v_lshlrev_b32_e32 v72, 16, v34
	v_and_b32_e32 v73, 0xffff0000, v34
	v_lshlrev_b32_e32 v70, 16, v35
	v_and_b32_e32 v71, 0xffff0000, v35
	v_lshlrev_b32_e32 v2, 16, v33
	v_and_b32_e32 v3, 0xffff0000, v33
	v_sub_f32_e32 v69, v68, v65
	v_sub_f32_e32 v68, v0, v64
	v_sub_f32_e32 v71, v71, v59
	v_sub_f32_e32 v70, v70, v58
	v_sub_f32_e32 v73, v73, v57
	v_sub_f32_e32 v72, v72, v56
	v_sub_f32_e32 v3, v3, v67
	v_sub_f32_e32 v2, v2, v66
	v_pk_mul_f32 v[68:69], v[68:69], v[60:61]
	v_pk_mul_f32 v[72:73], v[72:73], v[52:53]
	v_pk_mul_f32 v[70:71], v[70:71], v[54:55]
	v_pk_mul_f32 v[2:3], v[2:3], v[62:63]
	v_pk_fma_f32 v[68:69], v[212:213], v[68:69], v[214:215] op_sel_hi:[0,1,0]
	v_pk_fma_f32 v[74:75], v[212:213], v[70:71], v[214:215] op_sel_hi:[0,1,0]
	v_pk_fma_f32 v[70:71], v[212:213], v[72:73], v[214:215] op_sel_hi:[0,1,0]
	v_pk_fma_f32 v[2:3], v[212:213], v[2:3], v[214:215] op_sel_hi:[0,1,0]
	v_cvt_pk_bf16_f32 v68, v68, v69
	v_cvt_pk_bf16_f32 v69, v2, v3
	v_cvt_pk_bf16_f32 v70, v70, v71
	v_cvt_pk_bf16_f32 v71, v74, v75
	v_add_u32_e32 v0, v161, v171
	ds_write_b128 v0, v[68:71]
	v_lshlrev_b32_e32 v0, 16, v36
	v_and_b32_e32 v68, 0xffff0000, v36
	v_lshlrev_b32_e32 v72, 16, v38
	v_and_b32_e32 v73, 0xffff0000, v38
	v_lshlrev_b32_e32 v70, 16, v39
	v_and_b32_e32 v71, 0xffff0000, v39
	v_lshlrev_b32_e32 v2, 16, v37
	v_and_b32_e32 v3, 0xffff0000, v37
	v_sub_f32_e32 v69, v68, v65
	v_sub_f32_e32 v68, v0, v64
	v_sub_f32_e32 v71, v71, v59
	v_sub_f32_e32 v70, v70, v58
	v_sub_f32_e32 v73, v73, v57
	v_sub_f32_e32 v72, v72, v56
	v_sub_f32_e32 v3, v3, v67
	v_sub_f32_e32 v2, v2, v66
	v_pk_mul_f32 v[68:69], v[68:69], v[60:61]
	v_pk_mul_f32 v[72:73], v[72:73], v[52:53]
	v_pk_mul_f32 v[70:71], v[70:71], v[54:55]
	v_pk_mul_f32 v[2:3], v[2:3], v[62:63]
	v_pk_fma_f32 v[68:69], v[218:219], v[68:69], v[222:223] op_sel_hi:[0,1,0]
	v_pk_fma_f32 v[74:75], v[218:219], v[70:71], v[222:223] op_sel_hi:[0,1,0]
	v_pk_fma_f32 v[70:71], v[218:219], v[72:73], v[222:223] op_sel_hi:[0,1,0]
	v_pk_fma_f32 v[2:3], v[218:219], v[2:3], v[222:223] op_sel_hi:[0,1,0]
	v_cvt_pk_bf16_f32 v68, v68, v69
	v_cvt_pk_bf16_f32 v69, v2, v3
	v_cvt_pk_bf16_f32 v70, v70, v71
	v_cvt_pk_bf16_f32 v71, v74, v75
	v_add_u32_e32 v0, v161, v175
	ds_write_b128 v0, v[68:71]
	v_lshlrev_b32_e32 v0, 16, v40
	v_and_b32_e32 v68, 0xffff0000, v40
	v_lshlrev_b32_e32 v72, 16, v42
	v_and_b32_e32 v73, 0xffff0000, v42
	v_lshlrev_b32_e32 v70, 16, v43
	v_and_b32_e32 v71, 0xffff0000, v43
	v_lshlrev_b32_e32 v2, 16, v41
	v_and_b32_e32 v3, 0xffff0000, v41
	v_sub_f32_e32 v69, v68, v65
	v_sub_f32_e32 v68, v0, v64
	v_sub_f32_e32 v71, v71, v59
	v_sub_f32_e32 v70, v70, v58
	v_sub_f32_e32 v73, v73, v57
	v_sub_f32_e32 v72, v72, v56
	v_sub_f32_e32 v3, v3, v67
	v_sub_f32_e32 v2, v2, v66
	v_pk_mul_f32 v[68:69], v[68:69], v[60:61]
	v_pk_mul_f32 v[72:73], v[72:73], v[52:53]
	v_pk_mul_f32 v[70:71], v[70:71], v[54:55]
	v_pk_mul_f32 v[2:3], v[2:3], v[62:63]
	v_pk_fma_f32 v[68:69], v[226:227], v[68:69], v[228:229] op_sel_hi:[0,1,0]
	v_pk_fma_f32 v[74:75], v[226:227], v[70:71], v[228:229] op_sel_hi:[0,1,0]
	v_pk_fma_f32 v[70:71], v[226:227], v[72:73], v[228:229] op_sel_hi:[0,1,0]
	v_pk_fma_f32 v[2:3], v[226:227], v[2:3], v[228:229] op_sel_hi:[0,1,0]
	v_cvt_pk_bf16_f32 v68, v68, v69
	v_cvt_pk_bf16_f32 v69, v2, v3
	v_cvt_pk_bf16_f32 v70, v70, v71
	v_cvt_pk_bf16_f32 v71, v74, v75
	v_add_u32_e32 v0, v161, v183
	ds_write_b128 v0, v[68:71]
	s_nop 0
	v_lshlrev_b32_e32 v0, 16, v44
	v_and_b32_e32 v68, 0xffff0000, v44
	v_lshlrev_b32_e32 v72, 16, v46
	v_and_b32_e32 v73, 0xffff0000, v46
	v_lshlrev_b32_e32 v70, 16, v47
	v_and_b32_e32 v71, 0xffff0000, v47
	v_lshlrev_b32_e32 v2, 16, v45
	v_and_b32_e32 v3, 0xffff0000, v45
	v_sub_f32_e32 v69, v68, v65
	v_sub_f32_e32 v68, v0, v64
	v_sub_f32_e32 v71, v71, v59
	v_sub_f32_e32 v70, v70, v58
	v_sub_f32_e32 v73, v73, v57
	v_sub_f32_e32 v72, v72, v56
	v_sub_f32_e32 v3, v3, v67
	v_sub_f32_e32 v2, v2, v66
	v_pk_mul_f32 v[68:69], v[68:69], v[60:61]
	v_pk_mul_f32 v[72:73], v[72:73], v[52:53]
	v_pk_mul_f32 v[70:71], v[70:71], v[54:55]
	v_pk_mul_f32 v[2:3], v[2:3], v[62:63]
	v_pk_fma_f32 v[68:69], v[232:233], v[68:69], v[234:235] op_sel_hi:[0,1,0]
	v_pk_fma_f32 v[74:75], v[232:233], v[70:71], v[234:235] op_sel_hi:[0,1,0]
	v_pk_fma_f32 v[70:71], v[232:233], v[72:73], v[234:235] op_sel_hi:[0,1,0]
	v_pk_fma_f32 v[2:3], v[232:233], v[2:3], v[234:235] op_sel_hi:[0,1,0]
	v_cvt_pk_bf16_f32 v68, v68, v69
	v_cvt_pk_bf16_f32 v69, v2, v3
	v_cvt_pk_bf16_f32 v70, v70, v71
	v_cvt_pk_bf16_f32 v71, v74, v75
	v_add_u32_e32 v0, v161, v187
	ds_write_b128 v0, v[68:71]
	s_nop 0
	v_lshlrev_b32_e32 v69, 16, v50
	v_and_b32_e32 v70, 0xffff0000, v50
	v_lshlrev_b32_e32 v71, 16, v51
	v_and_b32_e32 v72, 0xffff0000, v51
	v_lshlrev_b32_e32 v0, 16, v48
	v_and_b32_e32 v68, 0xffff0000, v48
	v_lshlrev_b32_e32 v2, 16, v49
	v_and_b32_e32 v3, 0xffff0000, v49
	v_sub_f32_e32 v59, v72, v59
	v_sub_f32_e32 v58, v71, v58
	v_sub_f32_e32 v57, v70, v57
	v_sub_f32_e32 v56, v69, v56
	v_sub_f32_e32 v3, v3, v67
	v_sub_f32_e32 v2, v2, v66
	v_sub_f32_e32 v65, v68, v65
	v_sub_f32_e32 v64, v0, v64
	v_pk_mul_f32 v[52:53], v[56:57], v[52:53]
	v_pk_mul_f32 v[54:55], v[58:59], v[54:55]
	v_pk_mul_f32 v[60:61], v[64:65], v[60:61]
	v_pk_mul_f32 v[2:3], v[2:3], v[62:63]
	s_nop 0
	v_pk_fma_f32 v[56:57], v[236:237], v[54:55], v[240:241] op_sel_hi:[0,1,0]
	v_pk_fma_f32 v[54:55], v[236:237], v[52:53], v[240:241] op_sel_hi:[0,1,0]
	v_add_u32_e32 v0, v161, v195
	v_pk_fma_f32 v[2:3], v[236:237], v[2:3], v[240:241] op_sel_hi:[0,1,0]
	v_pk_fma_f32 v[60:61], v[236:237], v[60:61], v[240:241] op_sel_hi:[0,1,0]
	v_cvt_pk_bf16_f32 v52, v60, v61
	v_cvt_pk_bf16_f32 v53, v2, v3
	v_cvt_pk_bf16_f32 v54, v54, v55
	v_cvt_pk_bf16_f32 v55, v56, v57
	ds_write_b128 v0, v[52:55]
	s_waitcnt lgkmcnt(0)
	s_barrier
	s_cmp_ge_i32 s22, s3
	s_cbranch_scc1 .LBB0_464
	s_add_i32 s11, s2, s10
	v_mad_i64_i32 v[2:3], s[24:25], s11, v241, v[196:197]
	v_mad_i64_i32 v[24:25], s[24:25], s11, v241, v[200:201]
	v_lshlrev_b64 v[2:3], 8, v[2:3]
	v_lshlrev_b64 v[24:25], 8, v[24:25]
	v_lshl_add_u64 v[2:3], v[140:141], 0, v[2:3]
	v_lshl_add_u64 v[32:33], v[140:141], 0, v[24:25]
	s_nop 0
	s_nop 0
	global_load_dwordx4 v[24:27], v[2:3], off
	s_nop 0
	global_load_dwordx4 v[32:35], v[32:33], off
	s_nop 0
	s_nop 0
	s_nop 0
	v_mad_i64_i32 v[2:3], s[24:25], s11, v241, v[210:211]
	v_mad_i64_i32 v[36:37], s[24:25], s11, v241, v[216:217]
	v_lshlrev_b64 v[2:3], 8, v[2:3]
	v_lshlrev_b64 v[36:37], 8, v[36:37]
	v_lshl_add_u64 v[2:3], v[140:141], 0, v[2:3]
	v_lshl_add_u64 v[40:41], v[140:141], 0, v[36:37]
	s_nop 0
	s_nop 0
	global_load_dwordx4 v[36:39], v[2:3], off
	s_nop 0
	global_load_dwordx4 v[40:43], v[40:41], off
	s_nop 0
	s_nop 0
	s_nop 0
	v_mad_i64_i32 v[2:3], s[24:25], s11, v241, v[220:221]
	v_mad_i64_i32 v[44:45], s[24:25], s11, v241, v[224:225]
	v_lshlrev_b64 v[2:3], 8, v[2:3]
	v_lshlrev_b64 v[44:45], 8, v[44:45]
	v_lshl_add_u64 v[2:3], v[140:141], 0, v[2:3]
	v_lshl_add_u64 v[48:49], v[140:141], 0, v[44:45]
	s_nop 0
	s_nop 0
	global_load_dwordx4 v[44:47], v[2:3], off
	s_nop 0
	global_load_dwordx4 v[48:51], v[48:49], off
	s_nop 0
	s_nop 0
	s_nop 0
